# mods_item 8 row loads issued together; norm_ffn phase: 4 rows of a wave with all loads in flight
# speedup vs baseline: 1.0426x; 1.0136x over previous
.LBB0_42:
	s_mov_b64 s[98:99], 0x6000
	v_lshl_add_u64 v[26:27], v[24:25], 0, s[0:1]
	global_load_dwordx4 v[96:99], v[26:27], off nt
	v_lshl_add_u64 v[128:129], v[26:27], 0, s[98:99]
	global_load_dwordx4 v[100:103], v[128:129], off nt
	v_lshl_add_u64 v[128:129], v[128:129], 0, s[98:99]
	global_load_dwordx4 v[104:107], v[128:129], off nt
	v_lshl_add_u64 v[128:129], v[128:129], 0, s[98:99]
	global_load_dwordx4 v[108:111], v[128:129], off nt
	v_lshl_add_u64 v[128:129], v[128:129], 0, s[98:99]
	global_load_dwordx4 v[112:115], v[128:129], off nt
	v_lshl_add_u64 v[128:129], v[128:129], 0, s[98:99]
	global_load_dwordx4 v[116:119], v[128:129], off nt
	v_lshl_add_u64 v[128:129], v[128:129], 0, s[98:99]
	global_load_dwordx4 v[120:123], v[128:129], off nt
	v_lshl_add_u64 v[128:129], v[128:129], 0, s[98:99]
	global_load_dwordx4 v[124:127], v[128:129], off nt
	ds_read_b128 v[42:45], v23
	ds_read_b128 v[16:19], v23 offset:16
	ds_read_b128 v[46:49], v23 offset:4096
	ds_read_b128 v[50:53], v23 offset:8192
	s_add_u32 s0, s0, 0x30000
	s_addc_u32 s1, s1, 0
	s_cmp_eq_u32 s0, 0x180000
	s_waitcnt vmcnt(7) lgkmcnt(3)
	v_mov_b64_e32 v[38:39], v[96:97]
	v_mov_b64_e32 v[40:41], v[98:99]
	v_pk_fma_f32 v[34:35], v[42:43], v[38:39], v[4:5] op_sel_hi:[0,1,1]
	v_pk_fma_f32 v[54:55], v[42:43], v[40:41], v[6:7] op_sel_hi:[0,1,1]
	s_waitcnt lgkmcnt(1)
	v_pk_fma_f32 v[12:13], v[38:39], v[46:47], v[12:13] op_sel_hi:[1,0,1]
	s_waitcnt lgkmcnt(0)
	v_pk_fma_f32 v[8:9], v[38:39], v[50:51], v[8:9] op_sel_hi:[1,0,1]
	v_pk_fma_f32 v[14:15], v[40:41], v[46:47], v[14:15] op_sel_hi:[1,0,1]
	v_pk_fma_f32 v[10:11], v[40:41], v[50:51], v[10:11] op_sel_hi:[1,0,1]
	v_mov_b32_e32 v40, v45
	s_waitcnt vmcnt(6)
	v_mov_b64_e32 v[4:5], v[100:101]
	v_mov_b64_e32 v[6:7], v[102:103]
	v_pk_fma_f32 v[34:35], v[42:43], v[4:5], v[34:35] op_sel:[1,0,0]
	v_pk_fma_f32 v[12:13], v[4:5], v[46:47], v[12:13] op_sel:[0,1,0]
	v_pk_fma_f32 v[8:9], v[4:5], v[50:51], v[8:9] op_sel:[0,1,0]
	v_pk_fma_f32 v[38:39], v[42:43], v[6:7], v[54:55] op_sel:[1,0,0]
	v_pk_fma_f32 v[14:15], v[6:7], v[46:47], v[14:15] op_sel:[0,1,0]
	v_pk_fma_f32 v[10:11], v[6:7], v[50:51], v[10:11] op_sel:[0,1,0]
	s_waitcnt vmcnt(5)
	v_mov_b64_e32 v[4:5], v[104:105]
	v_mov_b64_e32 v[6:7], v[106:107]
	v_pk_fma_f32 v[34:35], v[44:45], v[4:5], v[34:35] op_sel_hi:[0,1,1]
	v_pk_fma_f32 v[12:13], v[4:5], v[48:49], v[12:13] op_sel_hi:[1,0,1]
	v_pk_fma_f32 v[8:9], v[4:5], v[52:53], v[8:9] op_sel_hi:[1,0,1]
	v_pk_fma_f32 v[38:39], v[44:45], v[6:7], v[38:39] op_sel_hi:[0,1,1]
	v_pk_fma_f32 v[14:15], v[6:7], v[48:49], v[14:15] op_sel_hi:[1,0,1]
	v_pk_fma_f32 v[10:11], v[6:7], v[52:53], v[10:11] op_sel_hi:[1,0,1]
	s_waitcnt vmcnt(4)
	v_mov_b64_e32 v[4:5], v[108:109]
	v_mov_b64_e32 v[6:7], v[110:111]
	v_pk_fma_f32 v[42:43], v[40:41], v[6:7], v[38:39] op_sel_hi:[0,1,1]
	v_mov_b32_e32 v38, v49
	v_pk_fma_f32 v[12:13], v[4:5], v[38:39], v[12:13] op_sel_hi:[1,0,1]
	v_pk_fma_f32 v[14:15], v[6:7], v[38:39], v[14:15] op_sel_hi:[1,0,1]
	v_mov_b32_e32 v38, v53
	v_pk_fma_f32 v[34:35], v[40:41], v[4:5], v[34:35] op_sel_hi:[0,1,1]
	v_pk_fma_f32 v[44:45], v[4:5], v[38:39], v[8:9] op_sel_hi:[1,0,1]
	v_pk_fma_f32 v[46:47], v[6:7], v[38:39], v[10:11] op_sel_hi:[1,0,1]
	ds_read_b128 v[8:11], v23 offset:4112
	ds_read_b128 v[38:41], v23 offset:8208
	v_add_u32_e32 v23, 32, v23
	s_waitcnt vmcnt(3)
	v_mov_b64_e32 v[4:5], v[112:113]
	v_mov_b64_e32 v[6:7], v[114:115]
	v_pk_fma_f32 v[34:35], v[16:17], v[4:5], v[34:35] op_sel_hi:[0,1,1]
	s_waitcnt lgkmcnt(1)
	v_pk_fma_f32 v[12:13], v[4:5], v[8:9], v[12:13] op_sel_hi:[1,0,1]
	s_waitcnt lgkmcnt(0)
	v_pk_fma_f32 v[44:45], v[4:5], v[38:39], v[44:45] op_sel_hi:[1,0,1]
	v_pk_fma_f32 v[42:43], v[16:17], v[6:7], v[42:43] op_sel_hi:[0,1,1]
	v_pk_fma_f32 v[14:15], v[6:7], v[8:9], v[14:15] op_sel_hi:[1,0,1]
	v_pk_fma_f32 v[46:47], v[6:7], v[38:39], v[46:47] op_sel_hi:[1,0,1]
	s_waitcnt vmcnt(2)
	v_mov_b64_e32 v[4:5], v[116:117]
	v_mov_b64_e32 v[6:7], v[118:119]
	v_pk_fma_f32 v[34:35], v[16:17], v[4:5], v[34:35] op_sel:[1,0,0]
	v_pk_fma_f32 v[12:13], v[4:5], v[8:9], v[12:13] op_sel:[0,1,0]
	v_pk_fma_f32 v[8:9], v[6:7], v[8:9], v[14:15] op_sel:[0,1,0]
	v_pk_fma_f32 v[14:15], v[4:5], v[38:39], v[44:45] op_sel:[0,1,0]
	v_pk_fma_f32 v[16:17], v[16:17], v[6:7], v[42:43] op_sel:[1,0,0]
	v_pk_fma_f32 v[38:39], v[6:7], v[38:39], v[46:47] op_sel:[0,1,0]
	s_waitcnt vmcnt(1)
	v_mov_b64_e32 v[4:5], v[120:121]
	v_mov_b64_e32 v[6:7], v[122:123]
	v_pk_fma_f32 v[34:35], v[18:19], v[4:5], v[34:35] op_sel_hi:[0,1,1]
	v_pk_fma_f32 v[12:13], v[4:5], v[10:11], v[12:13] op_sel_hi:[1,0,1]
	v_pk_fma_f32 v[46:47], v[4:5], v[40:41], v[14:15] op_sel_hi:[1,0,1]
	v_pk_fma_f32 v[8:9], v[6:7], v[10:11], v[8:9] op_sel_hi:[1,0,1]
	v_mov_b32_e32 v10, v11
	v_pk_fma_f32 v[16:17], v[18:19], v[6:7], v[16:17] op_sel_hi:[0,1,1]
	v_pk_fma_f32 v[38:39], v[6:7], v[40:41], v[38:39] op_sel_hi:[1,0,1]
	v_mov_b32_e32 v6, v19
	s_waitcnt vmcnt(0)
	v_mov_b64_e32 v[42:43], v[124:125]
	v_mov_b64_e32 v[44:45], v[126:127]
	v_pk_fma_f32 v[12:13], v[42:43], v[10:11], v[12:13] op_sel_hi:[1,0,1]
	v_pk_fma_f32 v[14:15], v[44:45], v[10:11], v[8:9] op_sel_hi:[1,0,1]
	v_mov_b32_e32 v10, v41
	v_pk_fma_f32 v[4:5], v[6:7], v[42:43], v[34:35] op_sel_hi:[0,1,1]
	v_pk_fma_f32 v[6:7], v[6:7], v[44:45], v[16:17] op_sel_hi:[0,1,1]
	v_pk_fma_f32 v[8:9], v[42:43], v[10:11], v[46:47] op_sel_hi:[1,0,1]
	v_pk_fma_f32 v[10:11], v[44:45], v[10:11], v[38:39] op_sel_hi:[1,0,1]
	s_cbranch_scc0 .LBB0_42
	v_mul_u32_u24_e32 v16, 0x300, v32
	v_add3_u32 v2, v28, v16, v2
	v_cmp_lt_u32_sdwa s[2:3], v30, s61 src0_sel:BYTE_0 src1_sel:DWORD
	ds_write_b128 v2, v[4:7] offset:12288
	ds_write_b128 v2, v[12:15] offset:12544
	ds_write_b128 v2, v[8:11] offset:12800
	s_waitcnt lgkmcnt(0)
	s_barrier
	s_and_saveexec_b64 s[0:1], s[2:3]
	s_cbranch_execz .LBB0_45
	v_and_b32_e32 v2, 63, v30
	v_mad_u64_u32 v[4:5], s[2:3], v22, s67, v[20:21]
	v_or_b32_e32 v4, v2, v4
	v_ashrrev_i32_e32 v5, 31, v4
	v_lshl_add_u64 v[4:5], v[4:5], 2, s[14:15]
	global_load_dword v24, v[4:5], off
	ds_read2st64_b32 v[6:7], v31 offset0:48 offset1:60
	v_and_b32_e32 v5, 0xc0, v30
	v_lshrrev_b32_sdwa v4, v224, v30 dst_sel:DWORD dst_unused:UNUSED_PAD src0_sel:DWORD src1_sel:BYTE_0
	v_lshlrev_b32_e32 v12, 2, v5
	v_lshlrev_b32_e32 v2, 2, v2
	v_mov_b64_e32 v[10:11], s[30:31]
	v_mad_u64_u32 v[4:5], s[2:3], v22, 3, v[4:5]
	v_add3_u32 v22, v28, v12, v2
	s_waitcnt lgkmcnt(0)
	v_add_f32_e32 v6, 0, v6
	ds_read2st64_b32 v[8:9], v31 offset0:72 offset1:84
	v_mad_i64_i32 v[4:5], s[2:3], v4, s62, v[10:11]
	ds_read2st64_b32 v[10:11], v22 offset0:51 offset1:54
	ds_read2st64_b32 v[12:13], v22 offset0:57 offset1:63
	ds_read2st64_b32 v[14:15], v22 offset0:66 offset1:69
	ds_read2st64_b32 v[16:17], v22 offset0:75 offset1:78
	ds_read2st64_b32 v[18:19], v22 offset0:81 offset1:87
	ds_read2st64_b32 v[22:23], v22 offset0:90 offset1:93
	s_waitcnt lgkmcnt(5)
	v_add_f32_e32 v6, v6, v10
	v_add_f32_e32 v6, v6, v11
	s_waitcnt lgkmcnt(4)
	v_add_f32_e32 v6, v6, v12
	v_add_f32_e32 v6, v6, v7
	v_add_f32_e32 v6, v6, v13
	s_waitcnt lgkmcnt(3)
	v_add_f32_e32 v6, v6, v14
	v_add_f32_e32 v6, v6, v15
	v_add_f32_e32 v6, v6, v8
	s_waitcnt lgkmcnt(2)
	v_add_f32_e32 v6, v6, v16
	v_add_f32_e32 v6, v6, v17
	s_waitcnt lgkmcnt(1)
	v_add_f32_e32 v6, v6, v18
	v_add_f32_e32 v6, v6, v9
	v_add_f32_e32 v6, v6, v19
	s_waitcnt lgkmcnt(0)
	v_add_f32_e32 v6, v6, v22
	v_lshl_add_u64 v[4:5], v[20:21], 2, v[4:5]
	v_add_f32_e32 v6, v6, v23
	v_lshl_add_u64 v[4:5], v[4:5], 0, v[2:3]
	s_waitcnt vmcnt(0)
	v_add_f32_e32 v6, v6, v24
	global_store_dword v[4:5], v6, off

.LBB0_257:
	v_add_u32_e32 v1, s2, v28
	v_mov_b32_e32 v4, 0x2000
	v_cndmask_b32_e64 v1, v4, v1, s[0:1]
	v_cmp_lt_i32_e32 vcc, v28, v1
	s_and_saveexec_b64 s[0:1], vcc
	v_readlane_b32 s5, v254, 7
	s_movk_i32 s2, 0xfff
	s_mov_b64 s[14:15], 0x1000
	s_mul_i32 s16, s5, 3
	s_cbranch_execz .LBB0_260
	v_readlane_b32 s5, v254, 7
	s_lshl_b32 s8, s5, 10
	s_ashr_i32 s9, s8, 31
	s_lshl_b64 s[8:9], s[8:9], 2
	v_lshlrev_b32_e32 v4, 2, v2
	s_add_u32 s8, s6, s8
	v_and_b32_e32 v4, 0xfc, v4
	s_addc_u32 s9, s7, s9
	v_and_b32_e32 v5, 64, v223
	v_lshlrev_b32_e32 v6, 2, v4
	v_mov_b32_e32 v7, v3
	v_add_u32_e32 v5, 64, v5
	v_lshl_add_u64 v[30:31], s[8:9], 0, v[6:7]
	v_xor_b32_e32 v6, 32, v223
	v_cmp_lt_i32_e32 vcc, v6, v5
	s_load_dwordx2 s[10:11], s[30:31], 0x170
	v_ashrrev_i32_e32 v29, 31, v28
	v_cndmask_b32_e32 v6, v223, v6, vcc
	v_lshlrev_b32_e32 v37, 2, v6
	v_xor_b32_e32 v6, 16, v223
	v_cmp_lt_i32_e32 vcc, v6, v5
	v_lshlrev_b64 v[12:13], 11, v[28:29]
	v_and_b32_e32 v2, 63, v2
	v_cndmask_b32_e32 v6, v223, v6, vcc
	v_lshlrev_b32_e32 v56, 2, v6
	v_xor_b32_e32 v6, 8, v223
	v_cmp_lt_i32_e32 vcc, v6, v5
	v_readlane_b32 s8, v254, 16
	v_lshl_or_b32 v12, v2, 3, v12
	v_cndmask_b32_e32 v6, v223, v6, vcc
	v_lshlrev_b32_e32 v57, 2, v6
	v_xor_b32_e32 v6, 4, v223
	v_cmp_lt_i32_e32 vcc, v6, v5
	v_readlane_b32 s9, v254, 17
	s_add_u32 s6, s28, 0xd823000
	v_cndmask_b32_e32 v6, v223, v6, vcc
	v_lshlrev_b32_e32 v58, 2, v6
	v_xor_b32_e32 v6, 2, v223
	v_cmp_lt_i32_e32 vcc, v6, v5
	v_lshl_add_u64 v[32:33], s[8:9], 0, v[12:13]
	v_lshlrev_b64 v[12:13], 12, v[28:29]
	v_cndmask_b32_e32 v6, v223, v6, vcc
	v_lshlrev_b32_e32 v59, 2, v6
	v_xor_b32_e32 v6, 1, v223
	v_cmp_lt_i32_e32 vcc, v6, v5
	s_addc_u32 s7, s29, 0
	v_or_b32_e32 v8, 0x200, v4
	v_cndmask_b32_e32 v5, v223, v6, vcc
	v_or_b32_e32 v6, 0x100, v4
	v_or_b32_e32 v10, 0x300, v4
	s_ashr_i32 s5, s4, 31
	v_lshl_or_b32 v12, v2, 4, v12
	v_lshlrev_b32_e32 v60, 2, v5
	s_lshl_b64 s[8:9], s[4:5], 11
	s_waitcnt lgkmcnt(0)
	v_lshl_add_u64 v[34:35], s[10:11], 0, v[12:13]
	s_lshl_b64 s[10:11], s[4:5], 12
	s_mov_b64 s[12:13], 0
	v_lshlrev_b32_e32 v2, 2, v4
	v_lshlrev_b32_e32 v38, 2, v6
	v_lshlrev_b32_e32 v40, 2, v8
	v_lshlrev_b32_e32 v42, 2, v10
	v_sub_u32_e32 v4, v1, v28
	s_nop 0
	v_readfirstlane_b32 s5, v4
	s_cmp_eq_u32 s5, 4
	s_cbranch_scc0 .LBB0_259
	s_cmp_eq_u32 s4, 1
	s_cbranch_scc0 .LBB0_259
	v_cmp_gt_i32_e32 vcc, s67, v28
	s_nop 1
	v_cndmask_b32_e64 v4, 2, 1, vcc
	v_cmp_lt_i32_e32 vcc, s2, v28
	s_nop 1
	v_cndmask_b32_e32 v4, 0, v4, vcc
	v_add_u32_e32 v4, s16, v4
	v_mul_i32_i24_e32 v4, 0x6000, v4
	v_ashrrev_i32_e32 v5, 31, v4
	v_lshl_add_u64 v[146:147], s[6:7], 0, v[4:5]
	v_lshl_add_u64 v[148:149], v[146:147], 0, v[2:3]
	v_lshl_add_u64 v[150:151], v[148:149], 0, s[14:15]
	global_load_dwordx4 v[80:83], v[30:31], off
	global_load_dwordx4 v[84:87], v[30:31], off offset:1024
	global_load_dwordx4 v[88:91], v[30:31], off offset:2048
	global_load_dwordx4 v[92:95], v[30:31], off offset:3072
	global_load_dwordx4 v[96:99], v[148:149], off
	global_load_dwordx4 v[100:103], v[148:149], off offset:1024
	global_load_dwordx4 v[104:107], v[148:149], off offset:2048
	global_load_dwordx4 v[108:111], v[148:149], off offset:3072
	global_load_dwordx4 v[112:115], v[150:151], off
	global_load_dwordx4 v[116:119], v[150:151], off offset:1024
	global_load_dwordx4 v[120:123], v[150:151], off offset:2048
	global_load_dwordx4 v[124:127], v[150:151], off offset:3072
	global_load_dwordx4 v[188:191], v[34:35], off
	global_load_dwordx4 v[192:195], v[34:35], off offset:1024
	global_load_dwordx4 v[196:199], v[34:35], off offset:2048
	global_load_dwordx4 v[200:203], v[34:35], off offset:3072
	v_lshl_add_u64 v[152:153], v[34:35], 0, s[10:11]
	global_load_dwordx4 v[204:207], v[152:153], off
	global_load_dwordx4 v[208:211], v[152:153], off offset:1024
	global_load_dwordx4 v[212:215], v[152:153], off offset:2048
	global_load_dwordx4 v[234:237], v[152:153], off offset:3072
	v_lshl_add_u64 v[152:153], v[152:153], 0, s[10:11]
	global_load_dwordx4 v[238:241], v[152:153], off
	global_load_dwordx4 v[242:245], v[152:153], off offset:1024
	global_load_dwordx4 v[246:249], v[152:153], off offset:2048
	global_load_dwordx4 v[250:253], v[152:153], off offset:3072
	v_lshl_add_u64 v[152:153], v[152:153], 0, s[10:11]
	global_load_dwordx4 v[128:131], v[152:153], off
	global_load_dwordx4 v[132:135], v[152:153], off offset:1024
	global_load_dwordx4 v[136:139], v[152:153], off offset:2048
	global_load_dwordx4 v[142:145], v[152:153], off offset:3072
	s_waitcnt vmcnt(12)
	v_mul_f32_e32 v170, v189, v189
	v_fma_f32 v170, v188, v188, v170
	v_fma_f32 v170, v190, v190, v170
	v_fma_f32 v170, v191, v191, v170
	v_mul_f32_e32 v171, v193, v193
	v_fma_f32 v171, v192, v192, v171
	v_fma_f32 v171, v194, v194, v171
	v_fma_f32 v171, v195, v195, v171
	v_add_f32_e32 v158, v170, v171
	v_mul_f32_e32 v170, v197, v197
	v_fma_f32 v170, v196, v196, v170
	v_fma_f32 v170, v198, v198, v170
	v_fma_f32 v170, v199, v199, v170
	v_mul_f32_e32 v171, v201, v201
	v_fma_f32 v171, v200, v200, v171
	v_fma_f32 v171, v202, v202, v171
	v_fma_f32 v171, v203, v203, v171
	v_add_f32_e32 v158, v158, v170
	v_add_f32_e32 v158, v158, v171
	s_waitcnt vmcnt(8)
	v_mul_f32_e32 v170, v205, v205
	v_fma_f32 v170, v204, v204, v170
	v_fma_f32 v170, v206, v206, v170
	v_fma_f32 v170, v207, v207, v170
	v_mul_f32_e32 v171, v209, v209
	v_fma_f32 v171, v208, v208, v171
	v_fma_f32 v171, v210, v210, v171
	v_fma_f32 v171, v211, v211, v171
	v_add_f32_e32 v160, v170, v171
	v_mul_f32_e32 v170, v213, v213
	v_fma_f32 v170, v212, v212, v170
	v_fma_f32 v170, v214, v214, v170
	v_fma_f32 v170, v215, v215, v170
	v_mul_f32_e32 v171, v235, v235
	v_fma_f32 v171, v234, v234, v171
	v_fma_f32 v171, v236, v236, v171
	v_fma_f32 v171, v237, v237, v171
	v_add_f32_e32 v160, v160, v170
	v_add_f32_e32 v160, v160, v171
	s_waitcnt vmcnt(4)
	v_mul_f32_e32 v170, v239, v239
	v_fma_f32 v170, v238, v238, v170
	v_fma_f32 v170, v240, v240, v170
	v_fma_f32 v170, v241, v241, v170
	v_mul_f32_e32 v171, v243, v243
	v_fma_f32 v171, v242, v242, v171
	v_fma_f32 v171, v244, v244, v171
	v_fma_f32 v171, v245, v245, v171
	v_add_f32_e32 v162, v170, v171
	v_mul_f32_e32 v170, v247, v247
	v_fma_f32 v170, v246, v246, v170
	v_fma_f32 v170, v248, v248, v170
	v_fma_f32 v170, v249, v249, v170
	v_mul_f32_e32 v171, v251, v251
	v_fma_f32 v171, v250, v250, v171
	v_fma_f32 v171, v252, v252, v171
	v_fma_f32 v171, v253, v253, v171
	v_add_f32_e32 v162, v162, v170
	v_add_f32_e32 v162, v162, v171
	s_waitcnt vmcnt(0)
	v_mul_f32_e32 v170, v129, v129
	v_fma_f32 v170, v128, v128, v170
	v_fma_f32 v170, v130, v130, v170
	v_fma_f32 v170, v131, v131, v170
	v_mul_f32_e32 v171, v133, v133
	v_fma_f32 v171, v132, v132, v171
	v_fma_f32 v171, v134, v134, v171
	v_fma_f32 v171, v135, v135, v171
	v_add_f32_e32 v164, v170, v171
	v_mul_f32_e32 v170, v137, v137
	v_fma_f32 v170, v136, v136, v170
	v_fma_f32 v170, v138, v138, v170
	v_fma_f32 v170, v139, v139, v170
	v_mul_f32_e32 v171, v143, v143
	v_fma_f32 v171, v142, v142, v171
	v_fma_f32 v171, v144, v144, v171
	v_fma_f32 v171, v145, v145, v171
	v_add_f32_e32 v164, v164, v170
	v_add_f32_e32 v164, v164, v171
	ds_bpermute_b32 v166, v37, v158
	ds_bpermute_b32 v167, v37, v160
	ds_bpermute_b32 v168, v37, v162
	ds_bpermute_b32 v169, v37, v164
	s_waitcnt lgkmcnt(3)
	v_add_f32_e32 v158, v158, v166
	s_waitcnt lgkmcnt(2)
	v_add_f32_e32 v160, v160, v167
	s_waitcnt lgkmcnt(1)
	v_add_f32_e32 v162, v162, v168
	s_waitcnt lgkmcnt(0)
	v_add_f32_e32 v164, v164, v169
	ds_bpermute_b32 v166, v56, v158
	ds_bpermute_b32 v167, v56, v160
	ds_bpermute_b32 v168, v56, v162
	ds_bpermute_b32 v169, v56, v164
	s_waitcnt lgkmcnt(3)
	v_add_f32_e32 v158, v158, v166
	s_waitcnt lgkmcnt(2)
	v_add_f32_e32 v160, v160, v167
	s_waitcnt lgkmcnt(1)
	v_add_f32_e32 v162, v162, v168
	s_waitcnt lgkmcnt(0)
	v_add_f32_e32 v164, v164, v169
	ds_bpermute_b32 v166, v57, v158
	ds_bpermute_b32 v167, v57, v160
	ds_bpermute_b32 v168, v57, v162
	ds_bpermute_b32 v169, v57, v164
	s_waitcnt lgkmcnt(3)
	v_add_f32_e32 v158, v158, v166
	s_waitcnt lgkmcnt(2)
	v_add_f32_e32 v160, v160, v167
	s_waitcnt lgkmcnt(1)
	v_add_f32_e32 v162, v162, v168
	s_waitcnt lgkmcnt(0)
	v_add_f32_e32 v164, v164, v169
	ds_bpermute_b32 v166, v58, v158
	ds_bpermute_b32 v167, v58, v160
	ds_bpermute_b32 v168, v58, v162
	ds_bpermute_b32 v169, v58, v164
	s_waitcnt lgkmcnt(3)
	v_add_f32_e32 v158, v158, v166
	s_waitcnt lgkmcnt(2)
	v_add_f32_e32 v160, v160, v167
	s_waitcnt lgkmcnt(1)
	v_add_f32_e32 v162, v162, v168
	s_waitcnt lgkmcnt(0)
	v_add_f32_e32 v164, v164, v169
	ds_bpermute_b32 v166, v59, v158
	ds_bpermute_b32 v167, v59, v160
	ds_bpermute_b32 v168, v59, v162
	ds_bpermute_b32 v169, v59, v164
	s_waitcnt lgkmcnt(3)
	v_add_f32_e32 v158, v158, v166
	s_waitcnt lgkmcnt(2)
	v_add_f32_e32 v160, v160, v167
	s_waitcnt lgkmcnt(1)
	v_add_f32_e32 v162, v162, v168
	s_waitcnt lgkmcnt(0)
	v_add_f32_e32 v164, v164, v169
	ds_bpermute_b32 v166, v60, v158
	ds_bpermute_b32 v167, v60, v160
	ds_bpermute_b32 v168, v60, v162
	ds_bpermute_b32 v169, v60, v164
	s_waitcnt lgkmcnt(3)
	v_add_f32_e32 v158, v158, v166
	s_waitcnt lgkmcnt(2)
	v_add_f32_e32 v160, v160, v167
	s_waitcnt lgkmcnt(1)
	v_add_f32_e32 v162, v162, v168
	s_waitcnt lgkmcnt(0)
	v_add_f32_e32 v164, v164, v169
	v_pk_add_f32 v[112:113], v[112:113], 1.0 op_sel_hi:[1,0]
	v_pk_add_f32 v[114:115], v[114:115], 1.0 op_sel_hi:[1,0]
	v_pk_add_f32 v[116:117], v[116:117], 1.0 op_sel_hi:[1,0]
	v_pk_add_f32 v[118:119], v[118:119], 1.0 op_sel_hi:[1,0]
	v_pk_add_f32 v[120:121], v[120:121], 1.0 op_sel_hi:[1,0]
	v_pk_add_f32 v[122:123], v[122:123], 1.0 op_sel_hi:[1,0]
	v_pk_add_f32 v[124:125], v[124:125], 1.0 op_sel_hi:[1,0]
	v_pk_add_f32 v[126:127], v[126:127], 1.0 op_sel_hi:[1,0]
	v_fmamk_f32 v158, v158, 0x3a800000, v218
	v_cmp_gt_f32_e32 vcc, s71, v158
	v_mul_f32_e32 v170, 0x4b800000, v158
	s_nop 0
	v_cndmask_b32_e32 v158, v158, v170, vcc
	v_rsq_f32_e32 v158, v158
	s_nop 0
	v_mul_f32_e32 v170, 0x45800000, v158
	v_cndmask_b32_e32 v158, v158, v170, vcc
	v_fmamk_f32 v160, v160, 0x3a800000, v218
	v_cmp_gt_f32_e32 vcc, s71, v160
	v_mul_f32_e32 v170, 0x4b800000, v160
	s_nop 0
	v_cndmask_b32_e32 v160, v160, v170, vcc
	v_rsq_f32_e32 v160, v160
	s_nop 0
	v_mul_f32_e32 v170, 0x45800000, v160
	v_cndmask_b32_e32 v160, v160, v170, vcc
	v_fmamk_f32 v162, v162, 0x3a800000, v218
	v_cmp_gt_f32_e32 vcc, s71, v162
	v_mul_f32_e32 v170, 0x4b800000, v162
	s_nop 0
	v_cndmask_b32_e32 v162, v162, v170, vcc
	v_rsq_f32_e32 v162, v162
	s_nop 0
	v_mul_f32_e32 v170, 0x45800000, v162
	v_cndmask_b32_e32 v162, v162, v170, vcc
	v_fmamk_f32 v164, v164, 0x3a800000, v218
	v_cmp_gt_f32_e32 vcc, s71, v164
	v_mul_f32_e32 v170, 0x4b800000, v164
	s_nop 0
	v_cndmask_b32_e32 v164, v164, v170, vcc
	v_rsq_f32_e32 v164, v164
	s_nop 0
	v_mul_f32_e32 v170, 0x45800000, v164
	v_cndmask_b32_e32 v164, v164, v170, vcc
	v_pk_mul_f32 v[188:189], v[188:189], v[158:159] op_sel_hi:[1,0]
	v_pk_mul_f32 v[188:189], v[188:189], v[80:81]
	v_pk_fma_f32 v[188:189], v[188:189], v[112:113], v[96:97]
	v_pk_mul_f32 v[190:191], v[190:191], v[158:159] op_sel_hi:[1,0]
	v_pk_mul_f32 v[190:191], v[190:191], v[82:83]
	v_pk_fma_f32 v[190:191], v[190:191], v[114:115], v[98:99]
	v_cvt_pk_bf16_f32 v188, v188, v189
	v_cvt_pk_bf16_f32 v189, v190, v191
	global_store_dwordx2 v[32:33], v[188:189], off
	v_pk_mul_f32 v[192:193], v[192:193], v[158:159] op_sel_hi:[1,0]
	v_pk_mul_f32 v[192:193], v[192:193], v[84:85]
	v_pk_fma_f32 v[192:193], v[192:193], v[116:117], v[100:101]
	v_pk_mul_f32 v[194:195], v[194:195], v[158:159] op_sel_hi:[1,0]
	v_pk_mul_f32 v[194:195], v[194:195], v[86:87]
	v_pk_fma_f32 v[194:195], v[194:195], v[118:119], v[102:103]
	v_cvt_pk_bf16_f32 v192, v192, v193
	v_cvt_pk_bf16_f32 v193, v194, v195
	global_store_dwordx2 v[32:33], v[192:193], off offset:512
	v_pk_mul_f32 v[196:197], v[196:197], v[158:159] op_sel_hi:[1,0]
	v_pk_mul_f32 v[196:197], v[196:197], v[88:89]
	v_pk_fma_f32 v[196:197], v[196:197], v[120:121], v[104:105]
	v_pk_mul_f32 v[198:199], v[198:199], v[158:159] op_sel_hi:[1,0]
	v_pk_mul_f32 v[198:199], v[198:199], v[90:91]
	v_pk_fma_f32 v[198:199], v[198:199], v[122:123], v[106:107]
	v_cvt_pk_bf16_f32 v196, v196, v197
	v_cvt_pk_bf16_f32 v197, v198, v199
	global_store_dwordx2 v[32:33], v[196:197], off offset:1024
	v_pk_mul_f32 v[200:201], v[200:201], v[158:159] op_sel_hi:[1,0]
	v_pk_mul_f32 v[200:201], v[200:201], v[92:93]
	v_pk_fma_f32 v[200:201], v[200:201], v[124:125], v[108:109]
	v_pk_mul_f32 v[202:203], v[202:203], v[158:159] op_sel_hi:[1,0]
	v_pk_mul_f32 v[202:203], v[202:203], v[94:95]
	v_pk_fma_f32 v[202:203], v[202:203], v[126:127], v[110:111]
	v_cvt_pk_bf16_f32 v200, v200, v201
	v_cvt_pk_bf16_f32 v201, v202, v203
	global_store_dwordx2 v[32:33], v[200:201], off offset:1536
	v_lshl_add_u64 v[154:155], v[32:33], 0, s[8:9]
	v_pk_mul_f32 v[204:205], v[204:205], v[160:161] op_sel_hi:[1,0]
	v_pk_mul_f32 v[204:205], v[204:205], v[80:81]
	v_pk_fma_f32 v[204:205], v[204:205], v[112:113], v[96:97]
	v_pk_mul_f32 v[206:207], v[206:207], v[160:161] op_sel_hi:[1,0]
	v_pk_mul_f32 v[206:207], v[206:207], v[82:83]
	v_pk_fma_f32 v[206:207], v[206:207], v[114:115], v[98:99]
	v_cvt_pk_bf16_f32 v204, v204, v205
	v_cvt_pk_bf16_f32 v205, v206, v207
	global_store_dwordx2 v[154:155], v[204:205], off
	v_pk_mul_f32 v[208:209], v[208:209], v[160:161] op_sel_hi:[1,0]
	v_pk_mul_f32 v[208:209], v[208:209], v[84:85]
	v_pk_fma_f32 v[208:209], v[208:209], v[116:117], v[100:101]
	v_pk_mul_f32 v[210:211], v[210:211], v[160:161] op_sel_hi:[1,0]
	v_pk_mul_f32 v[210:211], v[210:211], v[86:87]
	v_pk_fma_f32 v[210:211], v[210:211], v[118:119], v[102:103]
	v_cvt_pk_bf16_f32 v208, v208, v209
	v_cvt_pk_bf16_f32 v209, v210, v211
	global_store_dwordx2 v[154:155], v[208:209], off offset:512
	v_pk_mul_f32 v[212:213], v[212:213], v[160:161] op_sel_hi:[1,0]
	v_pk_mul_f32 v[212:213], v[212:213], v[88:89]
	v_pk_fma_f32 v[212:213], v[212:213], v[120:121], v[104:105]
	v_pk_mul_f32 v[214:215], v[214:215], v[160:161] op_sel_hi:[1,0]
	v_pk_mul_f32 v[214:215], v[214:215], v[90:91]
	v_pk_fma_f32 v[214:215], v[214:215], v[122:123], v[106:107]
	v_cvt_pk_bf16_f32 v212, v212, v213
	v_cvt_pk_bf16_f32 v213, v214, v215
	global_store_dwordx2 v[154:155], v[212:213], off offset:1024
	v_pk_mul_f32 v[234:235], v[234:235], v[160:161] op_sel_hi:[1,0]
	v_pk_mul_f32 v[234:235], v[234:235], v[92:93]
	v_pk_fma_f32 v[234:235], v[234:235], v[124:125], v[108:109]
	v_pk_mul_f32 v[236:237], v[236:237], v[160:161] op_sel_hi:[1,0]
	v_pk_mul_f32 v[236:237], v[236:237], v[94:95]
	v_pk_fma_f32 v[236:237], v[236:237], v[126:127], v[110:111]
	v_cvt_pk_bf16_f32 v234, v234, v235
	v_cvt_pk_bf16_f32 v235, v236, v237
	global_store_dwordx2 v[154:155], v[234:235], off offset:1536
	v_lshl_add_u64 v[154:155], v[154:155], 0, s[8:9]
	v_pk_mul_f32 v[238:239], v[238:239], v[162:163] op_sel_hi:[1,0]
	v_pk_mul_f32 v[238:239], v[238:239], v[80:81]
	v_pk_fma_f32 v[238:239], v[238:239], v[112:113], v[96:97]
	v_pk_mul_f32 v[240:241], v[240:241], v[162:163] op_sel_hi:[1,0]
	v_pk_mul_f32 v[240:241], v[240:241], v[82:83]
	v_pk_fma_f32 v[240:241], v[240:241], v[114:115], v[98:99]
	v_cvt_pk_bf16_f32 v238, v238, v239
	v_cvt_pk_bf16_f32 v239, v240, v241
	global_store_dwordx2 v[154:155], v[238:239], off
	v_pk_mul_f32 v[242:243], v[242:243], v[162:163] op_sel_hi:[1,0]
	v_pk_mul_f32 v[242:243], v[242:243], v[84:85]
	v_pk_fma_f32 v[242:243], v[242:243], v[116:117], v[100:101]
	v_pk_mul_f32 v[244:245], v[244:245], v[162:163] op_sel_hi:[1,0]
	v_pk_mul_f32 v[244:245], v[244:245], v[86:87]
	v_pk_fma_f32 v[244:245], v[244:245], v[118:119], v[102:103]
	v_cvt_pk_bf16_f32 v242, v242, v243
	v_cvt_pk_bf16_f32 v243, v244, v245
	global_store_dwordx2 v[154:155], v[242:243], off offset:512
	v_pk_mul_f32 v[246:247], v[246:247], v[162:163] op_sel_hi:[1,0]
	v_pk_mul_f32 v[246:247], v[246:247], v[88:89]
	v_pk_fma_f32 v[246:247], v[246:247], v[120:121], v[104:105]
	v_pk_mul_f32 v[248:249], v[248:249], v[162:163] op_sel_hi:[1,0]
	v_pk_mul_f32 v[248:249], v[248:249], v[90:91]
	v_pk_fma_f32 v[248:249], v[248:249], v[122:123], v[106:107]
	v_cvt_pk_bf16_f32 v246, v246, v247
	v_cvt_pk_bf16_f32 v247, v248, v249
	global_store_dwordx2 v[154:155], v[246:247], off offset:1024
	v_pk_mul_f32 v[250:251], v[250:251], v[162:163] op_sel_hi:[1,0]
	v_pk_mul_f32 v[250:251], v[250:251], v[92:93]
	v_pk_fma_f32 v[250:251], v[250:251], v[124:125], v[108:109]
	v_pk_mul_f32 v[252:253], v[252:253], v[162:163] op_sel_hi:[1,0]
	v_pk_mul_f32 v[252:253], v[252:253], v[94:95]
	v_pk_fma_f32 v[252:253], v[252:253], v[126:127], v[110:111]
	v_cvt_pk_bf16_f32 v250, v250, v251
	v_cvt_pk_bf16_f32 v251, v252, v253
	global_store_dwordx2 v[154:155], v[250:251], off offset:1536
	v_lshl_add_u64 v[154:155], v[154:155], 0, s[8:9]
	v_pk_mul_f32 v[128:129], v[128:129], v[164:165] op_sel_hi:[1,0]
	v_pk_mul_f32 v[128:129], v[128:129], v[80:81]
	v_pk_fma_f32 v[128:129], v[128:129], v[112:113], v[96:97]
	v_pk_mul_f32 v[130:131], v[130:131], v[164:165] op_sel_hi:[1,0]
	v_pk_mul_f32 v[130:131], v[130:131], v[82:83]
	v_pk_fma_f32 v[130:131], v[130:131], v[114:115], v[98:99]
	v_cvt_pk_bf16_f32 v128, v128, v129
	v_cvt_pk_bf16_f32 v129, v130, v131
	global_store_dwordx2 v[154:155], v[128:129], off
	v_pk_mul_f32 v[132:133], v[132:133], v[164:165] op_sel_hi:[1,0]
	v_pk_mul_f32 v[132:133], v[132:133], v[84:85]
	v_pk_fma_f32 v[132:133], v[132:133], v[116:117], v[100:101]
	v_pk_mul_f32 v[134:135], v[134:135], v[164:165] op_sel_hi:[1,0]
	v_pk_mul_f32 v[134:135], v[134:135], v[86:87]
	v_pk_fma_f32 v[134:135], v[134:135], v[118:119], v[102:103]
	v_cvt_pk_bf16_f32 v132, v132, v133
	v_cvt_pk_bf16_f32 v133, v134, v135
	global_store_dwordx2 v[154:155], v[132:133], off offset:512
	v_pk_mul_f32 v[136:137], v[136:137], v[164:165] op_sel_hi:[1,0]
	v_pk_mul_f32 v[136:137], v[136:137], v[88:89]
	v_pk_fma_f32 v[136:137], v[136:137], v[120:121], v[104:105]
	v_pk_mul_f32 v[138:139], v[138:139], v[164:165] op_sel_hi:[1,0]
	v_pk_mul_f32 v[138:139], v[138:139], v[90:91]
	v_pk_fma_f32 v[138:139], v[138:139], v[122:123], v[106:107]
	v_cvt_pk_bf16_f32 v136, v136, v137
	v_cvt_pk_bf16_f32 v137, v138, v139
	global_store_dwordx2 v[154:155], v[136:137], off offset:1024
	v_pk_mul_f32 v[142:143], v[142:143], v[164:165] op_sel_hi:[1,0]
	v_pk_mul_f32 v[142:143], v[142:143], v[92:93]
	v_pk_fma_f32 v[142:143], v[142:143], v[124:125], v[108:109]
	v_pk_mul_f32 v[144:145], v[144:145], v[164:165] op_sel_hi:[1,0]
	v_pk_mul_f32 v[144:145], v[144:145], v[94:95]
	v_pk_fma_f32 v[144:145], v[144:145], v[126:127], v[110:111]
	v_cvt_pk_bf16_f32 v142, v142, v143
	v_cvt_pk_bf16_f32 v143, v144, v145
	global_store_dwordx2 v[154:155], v[142:143], off offset:1536
	s_branch .LBB0_260
